# P10 residual epilogue: 32 loads pipelined 15-deep with counted vmcnt instead of serialized load-wait-store pairs
# baseline (speedup 1.0000x reference)
;     __device__ __forceinline__ void operator()(const Acc& acc, const Unit& u, int wr, int wc, int fr, int fq) const {
; #pragma unroll
;         for (int bj = 0; bj < 2; ++bj) {
;             const int c = u.pn * 256 + bj * 128 + wc * 32 + 8 * fq;
; #pragma unroll
;             for (int ai = 0; ai < 2; ++ai)
; #pragma unroll
;                 for (int m = 0; m < 4; ++m) {
;                     const size_t off = (size_t)(u.pm * 256 + ai * 128 + wr * 64 + m * 16 + fr) * DM + c;
;                     const f32x4 r0 = *(const f32x4*)(res + off), r1 = *(const f32x4*)(res + off + 4);
;                     *(f32x4*)(out + off) = r0 + acc[ai][bj][m][0]; *(f32x4*)(out + off + 4) = r1 + acc[ai][bj][m][1];
;                 }
.LBB0_1730:
	v_lshl_or_b32 v152, s38, 8, v156
	v_lshl_or_b32 v150, s20, 8, v155
	v_readlane_b32 s48, v251, 4
	v_readlane_b32 s49, v251, 5
	v_lshlrev_b32_e32 v150, 2, v150
	v_lshl_or_b32 v144, v152, 13, v150
	s_and_b64 vcc, exec, s[4:5]
	s_mov_b64 s[4:5], -1
	v_readlane_b32 s50, v251, 6
	v_readlane_b32 s51, v251, 7
	s_mov_b64 s[20:21], s[48:49]
	v_add_u32_e32 v145, 0x20000, v144
	v_add_u32_e32 v146, 0x40000, v144
	v_add_u32_e32 v147, 0x60000, v144
	v_add_u32_e32 v148, 0x100000, v144
	v_add_u32_e32 v149, 0x120000, v144
	v_add_u32_e32 v150, 0x140000, v144
	v_add_u32_e32 v151, 0x160000, v144
	global_load_dwordx4 v[160:163], v144, s[48:49] offset:0
	global_load_dwordx4 v[164:167], v144, s[48:49] offset:16
	global_load_dwordx4 v[168:171], v145, s[48:49] offset:0
	global_load_dwordx4 v[172:175], v145, s[48:49] offset:16
	global_load_dwordx4 v[176:179], v146, s[48:49] offset:0
	global_load_dwordx4 v[180:183], v146, s[48:49] offset:16
	global_load_dwordx4 v[184:187], v147, s[48:49] offset:0
	global_load_dwordx4 v[188:191], v147, s[48:49] offset:16
	global_load_dwordx4 v[192:195], v148, s[48:49] offset:0
	global_load_dwordx4 v[196:199], v148, s[48:49] offset:16
	global_load_dwordx4 v[200:203], v149, s[48:49] offset:0
	global_load_dwordx4 v[204:207], v149, s[48:49] offset:16
	global_load_dwordx4 v[208:211], v150, s[48:49] offset:0
	global_load_dwordx4 v[212:215], v150, s[48:49] offset:16
	global_load_dwordx4 v[216:219], v151, s[48:49] offset:0
	s_waitcnt vmcnt(14)
	v_pk_add_f32 v[124:125], v[124:125], v[160:161]
	v_pk_add_f32 v[126:127], v[126:127], v[162:163]
	global_store_dwordx4 v144, v[124:127], s[16:17] offset:0
	global_load_dwordx4 v[160:163], v151, s[48:49] offset:16
	s_waitcnt vmcnt(15)
	v_pk_add_f32 v[120:121], v[120:121], v[164:165]
	v_pk_add_f32 v[122:123], v[122:123], v[166:167]
	global_store_dwordx4 v144, v[120:123], s[16:17] offset:16
	global_load_dwordx4 v[164:167], v144, s[48:49] offset:512
	s_waitcnt vmcnt(16)
	v_pk_add_f32 v[116:117], v[116:117], v[168:169]
	v_pk_add_f32 v[118:119], v[118:119], v[170:171]
	global_store_dwordx4 v145, v[116:119], s[16:17] offset:0
	global_load_dwordx4 v[168:171], v144, s[48:49] offset:528
	s_waitcnt vmcnt(17)
	v_pk_add_f32 v[112:113], v[112:113], v[172:173]
	v_pk_add_f32 v[114:115], v[114:115], v[174:175]
	global_store_dwordx4 v145, v[112:115], s[16:17] offset:16
	global_load_dwordx4 v[172:175], v145, s[48:49] offset:512
	s_waitcnt vmcnt(18)
	v_pk_add_f32 v[108:109], v[108:109], v[176:177]
	v_pk_add_f32 v[110:111], v[110:111], v[178:179]
	global_store_dwordx4 v146, v[108:111], s[16:17] offset:0
	global_load_dwordx4 v[176:179], v145, s[48:49] offset:528
	s_waitcnt vmcnt(19)
	v_pk_add_f32 v[104:105], v[104:105], v[180:181]
	v_pk_add_f32 v[106:107], v[106:107], v[182:183]
	global_store_dwordx4 v146, v[104:107], s[16:17] offset:16
	global_load_dwordx4 v[180:183], v146, s[48:49] offset:512
	s_waitcnt vmcnt(20)
	v_pk_add_f32 v[100:101], v[100:101], v[184:185]
	v_pk_add_f32 v[102:103], v[102:103], v[186:187]
	global_store_dwordx4 v147, v[100:103], s[16:17] offset:0
	global_load_dwordx4 v[184:187], v146, s[48:49] offset:528
	s_waitcnt vmcnt(21)
	v_pk_add_f32 v[96:97], v[96:97], v[188:189]
	v_pk_add_f32 v[98:99], v[98:99], v[190:191]
	global_store_dwordx4 v147, v[96:99], s[16:17] offset:16
	global_load_dwordx4 v[188:191], v147, s[48:49] offset:512
	s_waitcnt vmcnt(22)
	v_pk_add_f32 v[92:93], v[92:93], v[192:193]
	v_pk_add_f32 v[94:95], v[94:95], v[194:195]
	global_store_dwordx4 v148, v[92:95], s[16:17] offset:0
	global_load_dwordx4 v[192:195], v147, s[48:49] offset:528
	s_waitcnt vmcnt(23)
	v_pk_add_f32 v[88:89], v[88:89], v[196:197]
	v_pk_add_f32 v[90:91], v[90:91], v[198:199]
	global_store_dwordx4 v148, v[88:91], s[16:17] offset:16
	global_load_dwordx4 v[196:199], v148, s[48:49] offset:512
	s_waitcnt vmcnt(24)
	v_pk_add_f32 v[84:85], v[84:85], v[200:201]
	v_pk_add_f32 v[86:87], v[86:87], v[202:203]
	global_store_dwordx4 v149, v[84:87], s[16:17] offset:0
	global_load_dwordx4 v[200:203], v148, s[48:49] offset:528
	s_waitcnt vmcnt(25)
;     __device__ __forceinline__ void operator()(const Acc& acc, const Unit& u, int wr, int wc, int fr, int fq) const {
; #pragma unroll
;         for (int bj = 0; bj < 2; ++bj) {
;             const int c = u.pn * 256 + bj * 128 + wc * 32 + 8 * fq;
; #pragma unroll
;             for (int ai = 0; ai < 2; ++ai)
; #pragma unroll
;                 for (int m = 0; m < 4; ++m) {
;                     const size_t off = (size_t)(u.pm * 256 + ai * 128 + wr * 64 + m * 16 + fr) * DM + c;
;                     const f32x4 r0 = *(const f32x4*)(res + off), r1 = *(const f32x4*)(res + off + 4);
;                     *(f32x4*)(out + off) = r0 + acc[ai][bj][m][0]; *(f32x4*)(out + off + 4) = r1 + acc[ai][bj][m][1];
;                 }
	v_pk_add_f32 v[80:81], v[80:81], v[204:205]
	v_pk_add_f32 v[82:83], v[82:83], v[206:207]
	global_store_dwordx4 v149, v[80:83], s[16:17] offset:16
	global_load_dwordx4 v[204:207], v149, s[48:49] offset:512
	s_waitcnt vmcnt(26)
	v_pk_add_f32 v[72:73], v[72:73], v[208:209]
	v_pk_add_f32 v[74:75], v[74:75], v[210:211]
	global_store_dwordx4 v150, v[72:75], s[16:17] offset:0
	global_load_dwordx4 v[208:211], v149, s[48:49] offset:528
	s_waitcnt vmcnt(27)
	v_pk_add_f32 v[68:69], v[68:69], v[212:213]
	v_pk_add_f32 v[70:71], v[70:71], v[214:215]
	global_store_dwordx4 v150, v[68:71], s[16:17] offset:16
	global_load_dwordx4 v[212:215], v150, s[48:49] offset:512
	s_waitcnt vmcnt(28)
	v_pk_add_f32 v[60:61], v[60:61], v[216:217]
	v_pk_add_f32 v[62:63], v[62:63], v[218:219]
	global_store_dwordx4 v151, v[60:63], s[16:17] offset:0
	global_load_dwordx4 v[216:219], v150, s[48:49] offset:528
	s_waitcnt vmcnt(28)
	v_pk_add_f32 v[52:53], v[52:53], v[160:161]
	v_pk_add_f32 v[54:55], v[54:55], v[162:163]
	global_store_dwordx4 v151, v[52:55], s[16:17] offset:16
	global_load_dwordx4 v[160:163], v151, s[48:49] offset:512
	s_waitcnt vmcnt(28)
	v_pk_add_f32 v[76:77], v[76:77], v[164:165]
	v_pk_add_f32 v[78:79], v[78:79], v[166:167]
	global_store_dwordx4 v144, v[76:79], s[16:17] offset:512
	global_load_dwordx4 v[164:167], v151, s[48:49] offset:528
	s_waitcnt vmcnt(28)
	v_pk_add_f32 v[64:65], v[64:65], v[168:169]
	v_pk_add_f32 v[66:67], v[66:67], v[170:171]
	global_store_dwordx4 v144, v[64:67], s[16:17] offset:528
	s_waitcnt vmcnt(27)
	v_pk_add_f32 v[56:57], v[56:57], v[172:173]
	v_pk_add_f32 v[58:59], v[58:59], v[174:175]
	global_store_dwordx4 v145, v[56:59], s[16:17] offset:512
	s_waitcnt vmcnt(26)
	v_pk_add_f32 v[48:49], v[48:49], v[176:177]
	v_pk_add_f32 v[50:51], v[50:51], v[178:179]
	global_store_dwordx4 v145, v[48:51], s[16:17] offset:528
	s_waitcnt vmcnt(25)
	v_pk_add_f32 v[44:45], v[44:45], v[180:181]
	v_pk_add_f32 v[46:47], v[46:47], v[182:183]
	global_store_dwordx4 v146, v[44:47], s[16:17] offset:512
	s_waitcnt vmcnt(24)
	v_pk_add_f32 v[40:41], v[40:41], v[184:185]
	v_pk_add_f32 v[42:43], v[42:43], v[186:187]
	global_store_dwordx4 v146, v[40:43], s[16:17] offset:528
	s_waitcnt vmcnt(23)
	v_pk_add_f32 v[36:37], v[36:37], v[188:189]
	v_pk_add_f32 v[38:39], v[38:39], v[190:191]
	global_store_dwordx4 v147, v[36:39], s[16:17] offset:512
	s_waitcnt vmcnt(22)
	v_pk_add_f32 v[32:33], v[32:33], v[192:193]
	v_pk_add_f32 v[34:35], v[34:35], v[194:195]
	global_store_dwordx4 v147, v[32:35], s[16:17] offset:528
	s_waitcnt vmcnt(21)
	v_pk_add_f32 v[28:29], v[28:29], v[196:197]
	v_pk_add_f32 v[30:31], v[30:31], v[198:199]
	global_store_dwordx4 v148, v[28:31], s[16:17] offset:512
	s_waitcnt vmcnt(20)
	v_pk_add_f32 v[24:25], v[24:25], v[200:201]
	v_pk_add_f32 v[26:27], v[26:27], v[202:203]
	global_store_dwordx4 v148, v[24:27], s[16:17] offset:528
	s_waitcnt vmcnt(19)
	v_pk_add_f32 v[20:21], v[20:21], v[204:205]
	v_pk_add_f32 v[22:23], v[22:23], v[206:207]
	global_store_dwordx4 v149, v[20:23], s[16:17] offset:512
	s_waitcnt vmcnt(18)
	v_pk_add_f32 v[16:17], v[16:17], v[208:209]
	v_pk_add_f32 v[18:19], v[18:19], v[210:211]
	global_store_dwordx4 v149, v[16:19], s[16:17] offset:528
	s_waitcnt vmcnt(17)
	v_pk_add_f32 v[12:13], v[12:13], v[212:213]
	v_pk_add_f32 v[14:15], v[14:15], v[214:215]
	global_store_dwordx4 v150, v[12:15], s[16:17] offset:512
	s_waitcnt vmcnt(16)
	v_pk_add_f32 v[8:9], v[8:9], v[216:217]
	v_pk_add_f32 v[10:11], v[10:11], v[218:219]
	global_store_dwordx4 v150, v[8:11], s[16:17] offset:528
	s_waitcnt vmcnt(15)
	v_pk_add_f32 v[4:5], v[4:5], v[160:161]
	v_pk_add_f32 v[6:7], v[6:7], v[162:163]
	global_store_dwordx4 v151, v[4:7], s[16:17] offset:512
	s_waitcnt vmcnt(14)
	v_pk_add_f32 v[0:1], v[0:1], v[164:165]
	v_pk_add_f32 v[2:3], v[2:3], v[166:167]
	global_store_dwordx4 v151, v[0:3], s[16:17] offset:528
	s_cbranch_vccnz .LBB0_1717
	s_and_b64 vcc, exec, s[2:3]
	s_cbranch_vccnz .LBB0_1716
	s_barrier
	s_branch .LBB0_1716
